# batched chunk-scan loop; ssm_y staging/E/d_skip loads batched; odd WGs enter merge GEMMs 16us late
# speedup vs baseline: 1.0188x; 1.0188x over previous
; __device__ __forceinline__ unsigned cvt_pk_bf16(float lo, float hi) { unsigned r; asm volatile("v_cvt_pk_bf16_f32 %0, %1, %2" : "=v"(r) : "v"(lo), "v"(hi)); return r; }
; __device__ __forceinline__ void ssm_scan(const Params& P, int gt) {
;     const int b = gt >> 12, g = (gt >> 6) & 63, p = gt & 63;
;     const f32x2 a = *(const f32x2*)((const float*)(P.ws + WS_A64) + (g * 64 + p) * 2);
;     const float* xl = (const float*)(P.ws + WS_XLOC) + ((size_t)(b * 256) * 64 + g) * 128 + 2 * p;
;     unsigned* xs = (unsigned*)((bf16_t*)(P.ws + WS_XS) + ((size_t)(b * 256) * 64 + g) * 128 + 2 * p);
;     float xr = 0.f, xi = 0.f;
; #pragma unroll 32
;     for (int c = 0; c < 256; ++c) {
;         const f32x2 l = *(const f32x2*)(xl + (size_t)c * 64 * 128);
;         xs[(size_t)c * 64 * 64] = cvt_pk_bf16(xr, xi);
;         const float nr = a[0] * xr - a[1] * xi + l[0], ni = a[0] * xi + a[1] * xr + l[1]; xr = nr; xi = ni;
;     }
; }
.LBB0_313:
	s_and_b32 s14, s9, 0xffffff00
	s_ashr_i32 s15, s14, 31
	s_lshl_b64 s[16:17], s[14:15], 14
	s_lshl_b32 s4, s10, 1
	v_or_b32_e32 v4, s16, v0
	s_and_b32 s4, s4, 0x3f00
	v_or_b32_e32 v4, s4, v4
	s_lshl_b64 s[14:15], s[14:15], 15
	s_lshl_b32 s4, s10, 2
	v_or_b32_e32 v6, s14, v2
	s_and_b32 s4, s4, 0x7e00
	v_or_b32_e32 v6, s4, v6
	s_lshl_b32 s4, s8, 7
	s_and_b32 s4, s4, 0x1f80
	v_or_b32_e32 v8, s4, v3
	v_lshlrev_b32_e32 v162, 2, v8
	v_lshl_add_u64 v[8:9], s[6:7], 0, v[162:163]
	flat_load_dwordx2 v[8:9], v[8:9]
	v_mov_b32_e32 v16, 0
	v_mov_b32_e32 v5, s17
	v_mov_b32_e32 v7, s15
	s_movk_i32 s14, 0x100
	v_mov_b32_e32 v17, v16
	s_waitcnt vmcnt(0) lgkmcnt(0)
	v_pk_mov_b32 v[10:11], v[8:9], v[8:9] op_sel:[1,0]
	v_add_u32_e32 v18, 0x1100000, v6
	v_add_u32_e32 v19, 0x3a400000, v4
.LBB0_314:
	global_load_dwordx2 v[24:25], v18, s[2:3]
	v_add_u32_e32 v18, 0x8000, v18
	global_load_dwordx2 v[26:27], v18, s[2:3]
	v_add_u32_e32 v18, 0x8000, v18
	global_load_dwordx2 v[28:29], v18, s[2:3]
	v_add_u32_e32 v18, 0x8000, v18
	global_load_dwordx2 v[30:31], v18, s[2:3]
	v_add_u32_e32 v18, 0x8000, v18
	global_load_dwordx2 v[32:33], v18, s[2:3]
	v_add_u32_e32 v18, 0x8000, v18
	global_load_dwordx2 v[34:35], v18, s[2:3]
	v_add_u32_e32 v18, 0x8000, v18
	global_load_dwordx2 v[36:37], v18, s[2:3]
	v_add_u32_e32 v18, 0x8000, v18
	global_load_dwordx2 v[38:39], v18, s[2:3]
	v_add_u32_e32 v18, 0x8000, v18
	global_load_dwordx2 v[40:41], v18, s[2:3]
	v_add_u32_e32 v18, 0x8000, v18
	global_load_dwordx2 v[42:43], v18, s[2:3]
	v_add_u32_e32 v18, 0x8000, v18
	global_load_dwordx2 v[44:45], v18, s[2:3]
	v_add_u32_e32 v18, 0x8000, v18
	global_load_dwordx2 v[46:47], v18, s[2:3]
	v_add_u32_e32 v18, 0x8000, v18
	global_load_dwordx2 v[48:49], v18, s[2:3]
	v_add_u32_e32 v18, 0x8000, v18
	global_load_dwordx2 v[50:51], v18, s[2:3]
	v_add_u32_e32 v18, 0x8000, v18
	global_load_dwordx2 v[52:53], v18, s[2:3]
	v_add_u32_e32 v18, 0x8000, v18
	global_load_dwordx2 v[54:55], v18, s[2:3]
	v_add_u32_e32 v18, 0x8000, v18
	global_load_dwordx2 v[56:57], v18, s[2:3]
	v_add_u32_e32 v18, 0x8000, v18
	global_load_dwordx2 v[58:59], v18, s[2:3]
	v_add_u32_e32 v18, 0x8000, v18
	global_load_dwordx2 v[60:61], v18, s[2:3]
	v_add_u32_e32 v18, 0x8000, v18
	global_load_dwordx2 v[62:63], v18, s[2:3]
	v_add_u32_e32 v18, 0x8000, v18
	global_load_dwordx2 v[64:65], v18, s[2:3]
	v_add_u32_e32 v18, 0x8000, v18
	global_load_dwordx2 v[66:67], v18, s[2:3]
	v_add_u32_e32 v18, 0x8000, v18
	global_load_dwordx2 v[68:69], v18, s[2:3]
	v_add_u32_e32 v18, 0x8000, v18
	global_load_dwordx2 v[70:71], v18, s[2:3]
	v_add_u32_e32 v18, 0x8000, v18
	global_load_dwordx2 v[72:73], v18, s[2:3]
	v_add_u32_e32 v18, 0x8000, v18
	global_load_dwordx2 v[74:75], v18, s[2:3]
	v_add_u32_e32 v18, 0x8000, v18
	global_load_dwordx2 v[76:77], v18, s[2:3]
	v_add_u32_e32 v18, 0x8000, v18
	global_load_dwordx2 v[78:79], v18, s[2:3]
	v_add_u32_e32 v18, 0x8000, v18
	global_load_dwordx2 v[80:81], v18, s[2:3]
	v_add_u32_e32 v18, 0x8000, v18
	global_load_dwordx2 v[82:83], v18, s[2:3]
	v_add_u32_e32 v18, 0x8000, v18
	global_load_dwordx2 v[84:85], v18, s[2:3]
	v_add_u32_e32 v18, 0x8000, v18
	global_load_dwordx2 v[86:87], v18, s[2:3]
	v_add_u32_e32 v18, 0x8000, v18
	v_cvt_pk_bf16_f32 v88, v16, v17
	v_mul_f32_e32 v20, v9, v17
	v_mul_f32_e32 v21, v8, v17
	v_fma_f32 v20, v8, v16, -v20
	v_fma_f32 v21, v9, v16, v21
	s_waitcnt vmcnt(31)
	v_add_f32_e32 v16, v20, v24
	v_add_f32_e32 v17, v21, v25
	v_cvt_pk_bf16_f32 v89, v16, v17
	v_mul_f32_e32 v20, v9, v17
	v_mul_f32_e32 v21, v8, v17
	v_fma_f32 v20, v8, v16, -v20
	v_fma_f32 v21, v9, v16, v21
	s_waitcnt vmcnt(30)
	v_add_f32_e32 v16, v20, v26
	v_add_f32_e32 v17, v21, v27
	v_cvt_pk_bf16_f32 v90, v16, v17
	v_mul_f32_e32 v20, v9, v17
	v_mul_f32_e32 v21, v8, v17
	v_fma_f32 v20, v8, v16, -v20
	v_fma_f32 v21, v9, v16, v21
	s_waitcnt vmcnt(29)
	v_add_f32_e32 v16, v20, v28
	v_add_f32_e32 v17, v21, v29
	v_cvt_pk_bf16_f32 v91, v16, v17
	v_mul_f32_e32 v20, v9, v17
	v_mul_f32_e32 v21, v8, v17
	v_fma_f32 v20, v8, v16, -v20
	v_fma_f32 v21, v9, v16, v21
	s_waitcnt vmcnt(28)
	v_add_f32_e32 v16, v20, v30
	v_add_f32_e32 v17, v21, v31
	v_cvt_pk_bf16_f32 v92, v16, v17
	v_mul_f32_e32 v20, v9, v17
	v_mul_f32_e32 v21, v8, v17
	v_fma_f32 v20, v8, v16, -v20
	v_fma_f32 v21, v9, v16, v21
	s_waitcnt vmcnt(27)
	v_add_f32_e32 v16, v20, v32
	v_add_f32_e32 v17, v21, v33
	v_cvt_pk_bf16_f32 v93, v16, v17
	v_mul_f32_e32 v20, v9, v17
	v_mul_f32_e32 v21, v8, v17
	v_fma_f32 v20, v8, v16, -v20
	v_fma_f32 v21, v9, v16, v21
	s_waitcnt vmcnt(26)
	v_add_f32_e32 v16, v20, v34
	v_add_f32_e32 v17, v21, v35
	v_cvt_pk_bf16_f32 v94, v16, v17
	v_mul_f32_e32 v20, v9, v17
	v_mul_f32_e32 v21, v8, v17
	v_fma_f32 v20, v8, v16, -v20
	v_fma_f32 v21, v9, v16, v21
	s_waitcnt vmcnt(25)
	v_add_f32_e32 v16, v20, v36
	v_add_f32_e32 v17, v21, v37
	v_cvt_pk_bf16_f32 v95, v16, v17
	v_mul_f32_e32 v20, v9, v17
	v_mul_f32_e32 v21, v8, v17
	v_fma_f32 v20, v8, v16, -v20
	v_fma_f32 v21, v9, v16, v21
	s_waitcnt vmcnt(24)
	v_add_f32_e32 v16, v20, v38
	v_add_f32_e32 v17, v21, v39
	v_cvt_pk_bf16_f32 v96, v16, v17
	v_mul_f32_e32 v20, v9, v17
	v_mul_f32_e32 v21, v8, v17
	v_fma_f32 v20, v8, v16, -v20
	v_fma_f32 v21, v9, v16, v21
	s_waitcnt vmcnt(23)
	v_add_f32_e32 v16, v20, v40
	v_add_f32_e32 v17, v21, v41
	v_cvt_pk_bf16_f32 v97, v16, v17
	v_mul_f32_e32 v20, v9, v17
	v_mul_f32_e32 v21, v8, v17
	v_fma_f32 v20, v8, v16, -v20
	v_fma_f32 v21, v9, v16, v21
	s_waitcnt vmcnt(22)
	v_add_f32_e32 v16, v20, v42
	v_add_f32_e32 v17, v21, v43
	v_cvt_pk_bf16_f32 v98, v16, v17
	v_mul_f32_e32 v20, v9, v17
	v_mul_f32_e32 v21, v8, v17
	v_fma_f32 v20, v8, v16, -v20
	v_fma_f32 v21, v9, v16, v21
	s_waitcnt vmcnt(21)
; __device__ __forceinline__ unsigned cvt_pk_bf16(float lo, float hi) { unsigned r; asm volatile("v_cvt_pk_bf16_f32 %0, %1, %2" : "=v"(r) : "v"(lo), "v"(hi)); return r; }
; __device__ __forceinline__ void ssm_scan(const Params& P, int gt) {
;     ...
;     for (int c = 0; c < 256; ++c) {
;         const f32x2 l = *(const f32x2*)(xl + (size_t)c * 64 * 128);
;         xs[(size_t)c * 64 * 64] = cvt_pk_bf16(xr, xi);
;         const float nr = a[0] * xr - a[1] * xi + l[0], ni = a[0] * xi + a[1] * xr + l[1]; xr = nr; xi = ni;
;     }
	v_add_f32_e32 v16, v20, v44
	v_add_f32_e32 v17, v21, v45
	v_cvt_pk_bf16_f32 v99, v16, v17
	v_mul_f32_e32 v20, v9, v17
	v_mul_f32_e32 v21, v8, v17
	v_fma_f32 v20, v8, v16, -v20
	v_fma_f32 v21, v9, v16, v21
	s_waitcnt vmcnt(20)
	v_add_f32_e32 v16, v20, v46
	v_add_f32_e32 v17, v21, v47
	v_cvt_pk_bf16_f32 v100, v16, v17
	v_mul_f32_e32 v20, v9, v17
	v_mul_f32_e32 v21, v8, v17
	v_fma_f32 v20, v8, v16, -v20
	v_fma_f32 v21, v9, v16, v21
	s_waitcnt vmcnt(19)
	v_add_f32_e32 v16, v20, v48
	v_add_f32_e32 v17, v21, v49
	v_cvt_pk_bf16_f32 v101, v16, v17
	v_mul_f32_e32 v20, v9, v17
	v_mul_f32_e32 v21, v8, v17
	v_fma_f32 v20, v8, v16, -v20
	v_fma_f32 v21, v9, v16, v21
	s_waitcnt vmcnt(18)
	v_add_f32_e32 v16, v20, v50
	v_add_f32_e32 v17, v21, v51
	v_cvt_pk_bf16_f32 v102, v16, v17
	v_mul_f32_e32 v20, v9, v17
	v_mul_f32_e32 v21, v8, v17
	v_fma_f32 v20, v8, v16, -v20
	v_fma_f32 v21, v9, v16, v21
	s_waitcnt vmcnt(17)
	v_add_f32_e32 v16, v20, v52
	v_add_f32_e32 v17, v21, v53
	v_cvt_pk_bf16_f32 v103, v16, v17
	v_mul_f32_e32 v20, v9, v17
	v_mul_f32_e32 v21, v8, v17
	v_fma_f32 v20, v8, v16, -v20
	v_fma_f32 v21, v9, v16, v21
	s_waitcnt vmcnt(16)
	v_add_f32_e32 v16, v20, v54
	v_add_f32_e32 v17, v21, v55
	v_cvt_pk_bf16_f32 v104, v16, v17
	v_mul_f32_e32 v20, v9, v17
	v_mul_f32_e32 v21, v8, v17
	v_fma_f32 v20, v8, v16, -v20
	v_fma_f32 v21, v9, v16, v21
	s_waitcnt vmcnt(15)
	v_add_f32_e32 v16, v20, v56
	v_add_f32_e32 v17, v21, v57
	v_cvt_pk_bf16_f32 v105, v16, v17
	v_mul_f32_e32 v20, v9, v17
	v_mul_f32_e32 v21, v8, v17
	v_fma_f32 v20, v8, v16, -v20
	v_fma_f32 v21, v9, v16, v21
	s_waitcnt vmcnt(14)
	v_add_f32_e32 v16, v20, v58
	v_add_f32_e32 v17, v21, v59
	v_cvt_pk_bf16_f32 v106, v16, v17
	v_mul_f32_e32 v20, v9, v17
	v_mul_f32_e32 v21, v8, v17
	v_fma_f32 v20, v8, v16, -v20
	v_fma_f32 v21, v9, v16, v21
	s_waitcnt vmcnt(13)
	v_add_f32_e32 v16, v20, v60
	v_add_f32_e32 v17, v21, v61
	v_cvt_pk_bf16_f32 v107, v16, v17
	v_mul_f32_e32 v20, v9, v17
	v_mul_f32_e32 v21, v8, v17
	v_fma_f32 v20, v8, v16, -v20
	v_fma_f32 v21, v9, v16, v21
	s_waitcnt vmcnt(12)
	v_add_f32_e32 v16, v20, v62
	v_add_f32_e32 v17, v21, v63
	v_cvt_pk_bf16_f32 v108, v16, v17
	v_mul_f32_e32 v20, v9, v17
	v_mul_f32_e32 v21, v8, v17
	v_fma_f32 v20, v8, v16, -v20
	v_fma_f32 v21, v9, v16, v21
	s_waitcnt vmcnt(11)
	v_add_f32_e32 v16, v20, v64
	v_add_f32_e32 v17, v21, v65
	v_cvt_pk_bf16_f32 v109, v16, v17
	v_mul_f32_e32 v20, v9, v17
	v_mul_f32_e32 v21, v8, v17
	v_fma_f32 v20, v8, v16, -v20
	v_fma_f32 v21, v9, v16, v21
	s_waitcnt vmcnt(10)
	v_add_f32_e32 v16, v20, v66
	v_add_f32_e32 v17, v21, v67
	v_cvt_pk_bf16_f32 v110, v16, v17
	v_mul_f32_e32 v20, v9, v17
	v_mul_f32_e32 v21, v8, v17
	v_fma_f32 v20, v8, v16, -v20
	v_fma_f32 v21, v9, v16, v21
	s_waitcnt vmcnt(9)
	v_add_f32_e32 v16, v20, v68
	v_add_f32_e32 v17, v21, v69
	v_cvt_pk_bf16_f32 v111, v16, v17
	v_mul_f32_e32 v20, v9, v17
	v_mul_f32_e32 v21, v8, v17
	v_fma_f32 v20, v8, v16, -v20
	v_fma_f32 v21, v9, v16, v21
	s_waitcnt vmcnt(8)
	v_add_f32_e32 v16, v20, v70
	v_add_f32_e32 v17, v21, v71
	v_cvt_pk_bf16_f32 v112, v16, v17
	v_mul_f32_e32 v20, v9, v17
	v_mul_f32_e32 v21, v8, v17
	v_fma_f32 v20, v8, v16, -v20
	v_fma_f32 v21, v9, v16, v21
	s_waitcnt vmcnt(7)
	v_add_f32_e32 v16, v20, v72
	v_add_f32_e32 v17, v21, v73
	v_cvt_pk_bf16_f32 v113, v16, v17
	v_mul_f32_e32 v20, v9, v17
	v_mul_f32_e32 v21, v8, v17
	v_fma_f32 v20, v8, v16, -v20
	v_fma_f32 v21, v9, v16, v21
	s_waitcnt vmcnt(6)
	v_add_f32_e32 v16, v20, v74
	v_add_f32_e32 v17, v21, v75
	v_cvt_pk_bf16_f32 v114, v16, v17
	v_mul_f32_e32 v20, v9, v17
	v_mul_f32_e32 v21, v8, v17
	v_fma_f32 v20, v8, v16, -v20
	v_fma_f32 v21, v9, v16, v21
	s_waitcnt vmcnt(5)
; __device__ __forceinline__ unsigned cvt_pk_bf16(float lo, float hi) { unsigned r; asm volatile("v_cvt_pk_bf16_f32 %0, %1, %2" : "=v"(r) : "v"(lo), "v"(hi)); return r; }
; __device__ __forceinline__ void ssm_scan(const Params& P, int gt) {
;     ...
;     for (int c = 0; c < 256; ++c) {
;         const f32x2 l = *(const f32x2*)(xl + (size_t)c * 64 * 128);
;         xs[(size_t)c * 64 * 64] = cvt_pk_bf16(xr, xi);
;         const float nr = a[0] * xr - a[1] * xi + l[0], ni = a[0] * xi + a[1] * xr + l[1]; xr = nr; xi = ni;
;     }
	v_add_f32_e32 v16, v20, v76
	v_add_f32_e32 v17, v21, v77
	v_cvt_pk_bf16_f32 v115, v16, v17
	v_mul_f32_e32 v20, v9, v17
	v_mul_f32_e32 v21, v8, v17
	v_fma_f32 v20, v8, v16, -v20
	v_fma_f32 v21, v9, v16, v21
	s_waitcnt vmcnt(4)
	v_add_f32_e32 v16, v20, v78
	v_add_f32_e32 v17, v21, v79
	v_cvt_pk_bf16_f32 v116, v16, v17
	v_mul_f32_e32 v20, v9, v17
	v_mul_f32_e32 v21, v8, v17
	v_fma_f32 v20, v8, v16, -v20
	v_fma_f32 v21, v9, v16, v21
	s_waitcnt vmcnt(3)
	v_add_f32_e32 v16, v20, v80
	v_add_f32_e32 v17, v21, v81
	v_cvt_pk_bf16_f32 v117, v16, v17
	v_mul_f32_e32 v20, v9, v17
	v_mul_f32_e32 v21, v8, v17
	v_fma_f32 v20, v8, v16, -v20
	v_fma_f32 v21, v9, v16, v21
	s_waitcnt vmcnt(2)
	v_add_f32_e32 v16, v20, v82
	v_add_f32_e32 v17, v21, v83
	v_cvt_pk_bf16_f32 v118, v16, v17
	v_mul_f32_e32 v20, v9, v17
	v_mul_f32_e32 v21, v8, v17
	v_fma_f32 v20, v8, v16, -v20
	v_fma_f32 v21, v9, v16, v21
	s_waitcnt vmcnt(1)
	v_add_f32_e32 v16, v20, v84
	v_add_f32_e32 v17, v21, v85
	v_cvt_pk_bf16_f32 v119, v16, v17
	v_mul_f32_e32 v20, v9, v17
	v_mul_f32_e32 v21, v8, v17
	v_fma_f32 v20, v8, v16, -v20
	v_fma_f32 v21, v9, v16, v21
	s_waitcnt vmcnt(0)
	v_add_f32_e32 v16, v20, v86
	v_add_f32_e32 v17, v21, v87
	global_store_dword v19, v88, s[2:3]
	v_add_u32_e32 v19, 0x4000, v19
	global_store_dword v19, v89, s[2:3]
	v_add_u32_e32 v19, 0x4000, v19
	global_store_dword v19, v90, s[2:3]
	v_add_u32_e32 v19, 0x4000, v19
	global_store_dword v19, v91, s[2:3]
	v_add_u32_e32 v19, 0x4000, v19
	global_store_dword v19, v92, s[2:3]
	v_add_u32_e32 v19, 0x4000, v19
	global_store_dword v19, v93, s[2:3]
	v_add_u32_e32 v19, 0x4000, v19
	global_store_dword v19, v94, s[2:3]
	v_add_u32_e32 v19, 0x4000, v19
	global_store_dword v19, v95, s[2:3]
	v_add_u32_e32 v19, 0x4000, v19
	global_store_dword v19, v96, s[2:3]
	v_add_u32_e32 v19, 0x4000, v19
	global_store_dword v19, v97, s[2:3]
	v_add_u32_e32 v19, 0x4000, v19
	global_store_dword v19, v98, s[2:3]
	v_add_u32_e32 v19, 0x4000, v19
	global_store_dword v19, v99, s[2:3]
	v_add_u32_e32 v19, 0x4000, v19
	global_store_dword v19, v100, s[2:3]
	v_add_u32_e32 v19, 0x4000, v19
	global_store_dword v19, v101, s[2:3]
	v_add_u32_e32 v19, 0x4000, v19
	global_store_dword v19, v102, s[2:3]
	v_add_u32_e32 v19, 0x4000, v19
	global_store_dword v19, v103, s[2:3]
	v_add_u32_e32 v19, 0x4000, v19
	global_store_dword v19, v104, s[2:3]
	v_add_u32_e32 v19, 0x4000, v19
	global_store_dword v19, v105, s[2:3]
	v_add_u32_e32 v19, 0x4000, v19
	global_store_dword v19, v106, s[2:3]
	v_add_u32_e32 v19, 0x4000, v19
	global_store_dword v19, v107, s[2:3]
	v_add_u32_e32 v19, 0x4000, v19
	global_store_dword v19, v108, s[2:3]
	v_add_u32_e32 v19, 0x4000, v19
	global_store_dword v19, v109, s[2:3]
	v_add_u32_e32 v19, 0x4000, v19
	global_store_dword v19, v110, s[2:3]
	v_add_u32_e32 v19, 0x4000, v19
	global_store_dword v19, v111, s[2:3]
	v_add_u32_e32 v19, 0x4000, v19
	global_store_dword v19, v112, s[2:3]
	v_add_u32_e32 v19, 0x4000, v19
	global_store_dword v19, v113, s[2:3]
	v_add_u32_e32 v19, 0x4000, v19
	global_store_dword v19, v114, s[2:3]
	v_add_u32_e32 v19, 0x4000, v19
	global_store_dword v19, v115, s[2:3]
	v_add_u32_e32 v19, 0x4000, v19
	global_store_dword v19, v116, s[2:3]
	v_add_u32_e32 v19, 0x4000, v19
	global_store_dword v19, v117, s[2:3]
	v_add_u32_e32 v19, 0x4000, v19
	global_store_dword v19, v118, s[2:3]
	v_add_u32_e32 v19, 0x4000, v19
	global_store_dword v19, v119, s[2:3]
	v_add_u32_e32 v19, 0x4000, v19
	s_sub_i32 s14, s14, 32
	s_cmp_lg_u32 s14, 0
	s_cbranch_scc1 .LBB0_314
	s_add_i32 s8, s8, s30
	s_add_i32 s9, s9, s26
	s_add_i32 s10, s10, s31
	s_cmpk_lt_i32 s8, 0x80
	s_cbranch_scc1 .LBB0_313

; #define LAS __attribute__((address_space(3)))
; __device__ __forceinline__ void ssm_y_unit(const Params& P, int li, LAS unsigned char* lds, int unit) {
;     ...
;     __syncthreads();
;     {
;         const u32x4* src = (const u32x4*)((const bf16_t*)(P.ws + WS_KTAB) + (size_t)g * 65 * 256);
;         for (int i = tid; i < 2080; i += 512) *(LAS u32x4*)(lds + SY_KT + i * 16) = src[i];
;         const bf16_t* U = (const bf16_t*)(P.ws + WS_U);
;         for (int i = tid; i < 4096; i += 512) { const int c = i >> 7, s = (i >> 1) & 63, hf = i & 1;
;             const u32x4 v = *(const u32x4*)(U + ((size_t)((cg_ * 32 + c) * 64 + s)) * 1024 + g * 16 + hf * 8);
;             *(LAS u32x4*)(lds + SY_U + c * SY_UP + s * 32 + hf * 16) = v; }
;     }
;     bf16x8 xsf[8];
;     { const bf16_t* xs = (const bf16_t*)(P.ws + WS_XS) + ((size_t)(cg_ * 32 + r32) * 64 + g) * 128 + hi * 8;
; #pragma unroll
;       for (int k = 0; k < 8; ++k) xsf[k] = *(const bf16x8*)(xs + k * 16); }
;     __syncthreads();
;     ...
;             const f32x4 d4 = *(const f32x4*)(dsk + h0);
.LBB0_378:
	v_mov_b32_e32 v0, v160
	s_ashr_i32 s20, s0, 4
	s_movk_i32 s18, 0x820
	s_ashr_i32 s21, s20, 31
	v_readfirstlane_b32 s4, v0
	v_cmp_gt_i32_e32 vcc, s18, v0
	s_barrier
	s_and_saveexec_b64 s[18:19], vcc
	s_cbranch_execz .LBB0_381
	s_mul_i32 s22, s20, 0x8200
	s_mul_hi_i32 s23, s20, 0x8200
	s_add_u32 s22, s30, s22
	v_ashrrev_i32_e32 v1, 31, v0
	s_addc_u32 s23, s31, s23
	v_add_u32_e32 v4, 0xfffffe00, v0
	v_lshl_add_u32 v5, v0, 4, 0
	v_lshl_add_u64 v[2:3], v[0:1], 4, s[22:23]
	s_mov_b64 s[22:23], 0
	s_mov_b64 s[34:35], 0x2000
	global_load_dwordx4 v[6:9], v[2:3], off
	v_lshl_add_u64 v[2:3], v[2:3], 0, s[34:35]
	global_load_dwordx4 v[10:13], v[2:3], off
	v_lshl_add_u64 v[2:3], v[2:3], 0, s[34:35]
	global_load_dwordx4 v[14:17], v[2:3], off
	v_lshl_add_u64 v[2:3], v[2:3], 0, s[34:35]
	global_load_dwordx4 v[18:21], v[2:3], off
	v_lshl_add_u64 v[2:3], v[2:3], 0, s[34:35]
	v_cmp_gt_u32_e32 vcc, 32, v0
	s_and_saveexec_b64 s[22:23], vcc
	s_cbranch_execz .Lsy_kt_ld_done
	global_load_dwordx4 v[22:25], v[2:3], off
.Lsy_kt_ld_done:
	s_mov_b64 exec, s[22:23]
	s_waitcnt vmcnt(0)
	ds_write_b128 v5, v[6:9]
	ds_write_b128 v5, v[10:13] offset:8192
	ds_write_b128 v5, v[14:17] offset:16384
	ds_write_b128 v5, v[18:21] offset:24576
	s_and_saveexec_b64 s[22:23], vcc
	s_cbranch_execz .Lsy_kt_st_done
	ds_write_b128 v5, v[22:25] offset:32768
.Lsy_kt_st_done:
	s_mov_b64 exec, s[22:23]
.LBB0_381:
	s_or_b64 exec, exec, s[18:19]
	s_movk_i32 s18, 0x1000
	v_cmp_gt_i32_e32 vcc, s18, v0
	s_lshl_b32 s18, s0, 11
	s_and_b32 s26, s18, 0x7800
	s_and_b32 s18, s0, -16
	s_ashr_i32 s19, s18, 31
	s_and_saveexec_b64 s[22:23], vcc
	s_cbranch_execz .LBB0_384
	s_lshl_b64 s[34:35], s[18:19], 1
	s_add_u32 s34, s1, s34
	v_lshlrev_b32_e32 v1, 4, v0
	s_addc_u32 s35, s8, s35
	v_and_b32_e32 v162, 16, v1
	v_lshl_add_u64 v[2:3], s[34:35], 0, v[162:163]
	s_mov_b64 s[38:39], 0
	v_mov_b32_e32 v1, v0
	v_ashrrev_i32_e32 v8, 7, v1
	v_bfe_u32 v9, v1, 1, 6
	v_lshl_add_u32 v4, v8, 6, s26
	v_or_b32_e32 v4, v4, v9
	v_ashrrev_i32_e32 v5, 31, v4
	v_lshlrev_b64 v[4:5], 11, v[4:5]
	v_lshl_add_u64 v[4:5], v[2:3], 0, v[4:5]
	v_mul_lo_u32 v8, v8, s25
	v_lshlrev_b32_e32 v9, 5, v9
	v_add3_u32 v8, v8, v9, v162
	s_mov_b64 s[42:43], 0x80000
	global_load_dwordx4 v[32:35], v[4:5], off
	v_lshl_add_u64 v[4:5], v[4:5], 0, s[42:43]
	global_load_dwordx4 v[36:39], v[4:5], off
	v_lshl_add_u64 v[4:5], v[4:5], 0, s[42:43]
	global_load_dwordx4 v[40:43], v[4:5], off
	v_lshl_add_u64 v[4:5], v[4:5], 0, s[42:43]
	global_load_dwordx4 v[44:47], v[4:5], off
	v_lshl_add_u64 v[4:5], v[4:5], 0, s[42:43]
	global_load_dwordx4 v[48:51], v[4:5], off
	v_lshl_add_u64 v[4:5], v[4:5], 0, s[42:43]
	global_load_dwordx4 v[52:55], v[4:5], off
	v_lshl_add_u64 v[4:5], v[4:5], 0, s[42:43]
	global_load_dwordx4 v[56:59], v[4:5], off
	v_lshl_add_u64 v[4:5], v[4:5], 0, s[42:43]
	global_load_dwordx4 v[60:63], v[4:5], off
	s_waitcnt vmcnt(0)
	ds_write_b128 v8, v[32:35] offset:33280
	v_add_u32_e32 v8, 0x2040, v8
	ds_write_b128 v8, v[36:39] offset:33280
	v_add_u32_e32 v8, 0x2040, v8
	ds_write_b128 v8, v[40:43] offset:33280
	v_add_u32_e32 v8, 0x2040, v8
	ds_write_b128 v8, v[44:47] offset:33280
	v_add_u32_e32 v8, 0x2040, v8
	ds_write_b128 v8, v[48:51] offset:33280
	v_add_u32_e32 v8, 0x2040, v8
	ds_write_b128 v8, v[52:55] offset:33280
	v_add_u32_e32 v8, 0x2040, v8
	ds_write_b128 v8, v[56:59] offset:33280
	v_add_u32_e32 v8, 0x2040, v8
	ds_write_b128 v8, v[60:63] offset:33280
.LBB0_384:
	s_or_b64 exec, exec, s[22:23]
	v_and_b32_e32 v1, 31, v0
	v_lshl_or_b32 v162, v1, 6, s26
	v_lshl_add_u64 v[2:3], v[162:163], 0, s[20:21]
	v_bfe_u32 v6, v0, 5, 1
	v_lshlrev_b64 v[2:3], 8, v[2:3]
	v_lshl_add_u64 v[2:3], s[2:3], 0, v[2:3]
	v_lshlrev_b32_e32 v4, 4, v6
	v_mov_b32_e32 v5, v163
	v_lshl_add_u64 v[2:3], v[2:3], 0, v[4:5]
	global_load_dwordx4 v[32:35], v[2:3], off
	global_load_dwordx4 v[36:39], v[2:3], off offset:32
	global_load_dwordx4 v[40:43], v[2:3], off offset:64
	global_load_dwordx4 v[44:47], v[2:3], off offset:96
	global_load_dwordx4 v[48:51], v[2:3], off offset:128
	global_load_dwordx4 v[52:55], v[2:3], off offset:160
	global_load_dwordx4 v[56:59], v[2:3], off offset:192
	global_load_dwordx4 v[60:63], v[2:3], off offset:224
	s_ashr_i32 s22, s4, 6
	s_lshl_b64 s[34:35], s[18:19], 2
	s_add_u32 s38, s9, s34
	v_bfe_u32 v74, v0, 4, 1
	v_lshlrev_b32_e32 v0, 5, v0
	v_lshlrev_b32_e32 v66, 2, v6
	s_addc_u32 s39, s10, s35
	v_mul_u32_u24_e32 v2, 0x810, v1
	v_and_b32_e32 v0, 0x1e0, v0
	s_lshl_b64 s[20:21], s[20:21], 10
	v_or_b32_e32 v70, 8, v66
	s_add_i32 s4, 0, 0x8200
	v_lshlrev_b32_e32 v71, 3, v6
	v_mad_u32_u24 v75, v1, s25, 0
	v_add3_u32 v76, 0, v0, v4
	v_or_b32_e32 v64, s20, v1
	v_mov_b32_e32 v65, s21
	s_sub_i32 s23, 15, s22
	s_add_i32 s34, s22, 16
	s_sub_i32 s35, 31, s22
	v_lshl_add_u64 v[68:69], s[38:39], 0, v[4:5]
	global_load_dwordx4 v[100:103], v[68:69], off
	global_load_dwordx4 v[104:107], v[68:69], off offset:32
	v_lshlrev_b32_e32 v77, 1, v70
	v_lshl_add_u64 v[72:73], s[6:7], 0, v[4:5]
	v_add3_u32 v78, v2, v4, s4
	v_lshlrev_b32_e32 v79, 9, v74
	s_mov_b32 s38, 0
	s_waitcnt lgkmcnt(0)
	s_barrier
	s_branch .LBB0_386
; #define LAS __attribute__((address_space(3)))
; __device__ __forceinline__ unsigned cvt_pk_bf16(float lo, float hi) { unsigned r; asm volatile("v_cvt_pk_bf16_f32 %0, %1, %2" : "=v"(r) : "v"(lo), "v"(hi)); return r; }
; __device__ __forceinline__ unsigned cvt4_fp8(float a, float b, float c, float d) { int v = 0; v = __builtin_amdgcn_cvt_pk_fp8_f32(a, b, v, false); v = __builtin_amdgcn_cvt_pk_fp8_f32(c, d, v, true); return (unsigned)v; }
; __device__ __forceinline__ float bf_lo(unsigned w) { return __uint_as_float(w << 16); }
; __device__ __forceinline__ float bf_hi(unsigned w) { return __uint_as_float(w & 0xffff0000u); }
; __device__ __forceinline__ float gelu_tanh(float y) { const float z = 1.5957691216057308f * (y + 0.044715f * y * y * y); return y * sigm(z); }
; __device__ __forceinline__ void ssm_y_unit(const Params& P, int li, LAS unsigned char* lds, int unit) {
;     ...
;         const bf16_t* E = (const bf16_t*)(P.ws + WS_ETAB) + ((size_t)g * 1024 + ti * 32 + r32) * 128 + hi * 8;
; #pragma unroll
;         for (int k = 0; k < 8; k += 2) { const bf16x8 a0 = *(const bf16x8*)(E + k * 16), a1 = *(const bf16x8*)(E + k * 16 + 16);
;             acc = __builtin_amdgcn_mfma_f32_32x32x16_bf16(a0, xsf[k], acc, 0, 0, 0); acc2 = __builtin_amdgcn_mfma_f32_32x32x16_bf16(a1, xsf[k + 1], acc2, 0, 0, 0); }
;         acc += acc2;
;         bf16_t* yg = (bf16_t*)(P.ws + WS_YG);
; #pragma unroll
;         for (int q = 0; q < 4; ++q) {
;             const int row = 8 * q + 4 * hi, t = 2 * ti + (row >> 4), h0 = row & 15;
;             const u32x2 uu = *(const LAS u32x2*)(lds + SY_U + r32 * SY_UP + t * 32 + h0 * 2);
;             const f32x4 d4 = *(const f32x4*)(dsk + h0);
;             float y0 = acc[4 * q] + d4[0] * bf_lo(uu[0]), y1 = acc[4 * q + 1] + d4[1] * bf_hi(uu[0]), y2 = acc[4 * q + 2] + d4[2] * bf_lo(uu[1]), y3 = acc[4 * q + 3] + d4[3] * bf_hi(uu[1]);
;             const float g0 = gelu_tanh(y0), g1 = gelu_tanh(y1), g2 = gelu_tanh(y2), g3 = gelu_tanh(y3);
;             u32x2 w; w.x = cvt_pk_bf16(g0, g1); w.y = cvt_pk_bf16(g2, g3);
;             const size_t yo = ((size_t)((cg_ * 32 + r32) * 64 + t)) * 1024 + g * 16 + h0;
;             *(u32x2*)(yg + yo) = w; *(unsigned*)(P.ws + WS_YG8 + yo) = cvt4_fp8(g0, g1, g2, g3);
;         }
.LBB0_385:
	s_lshl_b32 s40, s26, 5
	s_ashr_i32 s41, s40, 31
	v_lshl_add_u64 v[80:81], v[64:65], 0, s[40:41]
	v_lshlrev_b64 v[80:81], 8, v[80:81]
	v_lshl_add_u64 v[88:89], v[72:73], 0, v[80:81]
	s_or_b32 s4, s20, 1
	s_add_i32 s38, s38, 1
	s_cmp_eq_u32 s38, 4
	s_waitcnt vmcnt(6)
	v_mfma_f32_32x32x16_bf16 v[0:15], v[108:111], v[32:35], v[0:15]
	v_mfma_f32_32x32x16_bf16 v[16:31], v[112:115], v[36:39], v[16:31]
	s_waitcnt vmcnt(4)
	v_mfma_f32_32x32x16_bf16 v[0:15], v[116:119], v[40:43], v[0:15]
	v_mfma_f32_32x32x16_bf16 v[16:31], v[120:123], v[44:47], v[16:31]
	s_waitcnt vmcnt(2)
	v_mfma_f32_32x32x16_bf16 v[0:15], v[124:127], v[48:51], v[0:15]
	v_mfma_f32_32x32x16_bf16 v[16:31], v[128:131], v[52:55], v[16:31]
	s_waitcnt vmcnt(0)
	v_mfma_f32_32x32x16_bf16 v[0:15], v[132:135], v[56:59], v[0:15]
	v_mfma_f32_32x32x16_bf16 v[16:31], v[136:139], v[60:63], v[16:31]
	s_nop 11
	v_pk_add_f32 v[4:5], v[4:5], v[20:21]
	v_pk_add_f32 v[20:21], v[0:1], v[16:17]
	v_lshl_add_u32 v16, s26, 6, v75
	v_add_u32_e32 v0, v16, v71
	v_pk_add_f32 v[6:7], v[6:7], v[22:23]
	v_pk_add_f32 v[18:19], v[2:3], v[18:19]
	ds_read_b64 v[22:23], v0 offset:33280
	v_mov_b32_e32 v0, v100
	v_mov_b32_e32 v1, v101
	v_mov_b32_e32 v2, v102
	v_mov_b32_e32 v3, v103
	v_pk_add_f32 v[8:9], v[8:9], v[24:25]
	v_pk_add_f32 v[10:11], v[10:11], v[26:27]
	v_pk_add_f32 v[12:13], v[12:13], v[28:29]
	s_waitcnt lgkmcnt(0)
	v_lshlrev_b32_e32 v17, 16, v22
	v_pk_add_f32 v[14:15], v[14:15], v[30:31]
	v_fma_f32 v0, v0, v17, v20
	v_and_b32_e32 v17, 0xffff0000, v22
	v_fmac_f32_e32 v21, v1, v17
	v_lshlrev_b32_e32 v1, 16, v23
	v_fma_f32 v1, v2, v1, v18
	v_and_b32_e32 v2, 0xffff0000, v23
	v_fmac_f32_e32 v19, v3, v2
	v_mul_f32_e32 v2, 0x3d372713, v0
	v_mul_f32_e32 v2, v0, v2
	v_fma_f32 v2, v0, v2, v0
	v_mul_f32_e32 v2, 0x3fcc422a, v2
	v_mul_f32_e32 v2, 0xbfb8aa3b, v2
	v_exp_f32_e32 v2, v2
	s_nop 0
	v_add_f32_e32 v2, 1.0, v2
	v_rcp_f32_e32 v2, v2
	s_nop 0
	v_mul_f32_e32 v17, v0, v2
	v_mul_f32_e32 v0, 0x3d372713, v21
	v_mul_f32_e32 v0, v21, v0
	v_fma_f32 v0, v21, v0, v21
	v_mul_f32_e32 v0, 0x3fcc422a, v0
	v_mul_f32_e32 v0, 0xbfb8aa3b, v0
	v_exp_f32_e32 v0, v0
	s_nop 0
	v_add_f32_e32 v0, 1.0, v0
	v_rcp_f32_e32 v0, v0
	s_nop 0
	v_mul_f32_e32 v22, v21, v0
	v_mul_f32_e32 v0, 0x3d372713, v1
	v_mul_f32_e32 v0, v1, v0
	v_fma_f32 v0, v1, v0, v1
	v_mul_f32_e32 v0, 0x3fcc422a, v0
	v_mul_f32_e32 v0, 0xbfb8aa3b, v0
	v_exp_f32_e32 v0, v0
	v_cvt_pk_bf16_f32 v18, v17, v22
	s_nop 0
	v_add_f32_e32 v0, 1.0, v0
	v_rcp_f32_e32 v0, v0
	s_nop 0
	v_mul_f32_e32 v23, v1, v0
	v_mul_f32_e32 v0, 0x3d372713, v19
	v_mul_f32_e32 v0, v19, v0
	v_fma_f32 v0, v19, v0, v19
	v_mul_f32_e32 v0, 0x3fcc422a, v0
	v_mul_f32_e32 v0, 0xbfb8aa3b, v0
	v_exp_f32_e32 v0, v0
	s_nop 0
	v_add_f32_e32 v0, 1.0, v0
	v_rcp_f32_e32 v0, v0
	s_nop 0
	v_mul_f32_e32 v24, v19, v0
	v_add_u32_e32 v0, s20, v162
	v_ashrrev_i32_e32 v1, 31, v0
	v_lshlrev_b64 v[0:1], 10, v[0:1]
	v_lshl_add_u64 v[0:1], v[0:1], 0, s[18:19]
	v_or_b32_e32 v2, v0, v66
	v_mov_b32_e32 v3, v1
	v_lshl_add_u64 v[20:21], v[2:3], 1, s[14:15]
	v_cvt_pk_bf16_f32 v19, v23, v24
	global_store_dwordx2 v[20:21], v[18:19], off
	v_mov_b32_e32 v18, 0
	v_cvt_pk_fp8_f32 v18, v17, v22
	v_lshl_add_u64 v[2:3], s[16:17], 0, v[2:3]
	v_or_b32_e32 v0, v0, v70
	v_cvt_pk_fp8_f32 v18, v23, v24 op_sel:[0,0,1]
	global_store_dword v[2:3], v18, off
	v_add_u32_e32 v2, v16, v77
	v_mov_b32_e32 v16, v104
	v_mov_b32_e32 v17, v105
	v_mov_b32_e32 v18, v106
	v_mov_b32_e32 v19, v107
	ds_read_b64 v[2:3], v2 offset:33280
	s_waitcnt lgkmcnt(0)
	v_lshlrev_b32_e32 v20, 16, v2
	v_and_b32_e32 v2, 0xffff0000, v2
	v_fma_f32 v4, v16, v20, v4
	v_fmac_f32_e32 v5, v17, v2
	v_lshlrev_b32_e32 v2, 16, v3
	v_and_b32_e32 v3, 0xffff0000, v3
	v_fmac_f32_e32 v7, v19, v3
	v_mul_f32_e32 v3, 0x3d372713, v4
	v_mul_f32_e32 v3, v4, v3
	v_fma_f32 v3, v4, v3, v4
	v_mul_f32_e32 v3, 0x3fcc422a, v3
	v_mul_f32_e32 v3, 0xbfb8aa3b, v3
	v_exp_f32_e32 v3, v3
	v_fma_f32 v2, v18, v2, v6
	v_add_f32_e32 v3, 1.0, v3
	v_rcp_f32_e32 v3, v3
	s_nop 0
	v_mul_f32_e32 v6, v4, v3
	v_mul_f32_e32 v3, 0x3d372713, v5
	v_mul_f32_e32 v3, v5, v3
	v_fma_f32 v3, v5, v3, v5
	v_mul_f32_e32 v3, 0x3fcc422a, v3
	v_mul_f32_e32 v3, 0xbfb8aa3b, v3
	v_exp_f32_e32 v3, v3
	s_nop 0
	v_add_f32_e32 v3, 1.0, v3
	v_rcp_f32_e32 v3, v3
	s_nop 0
	v_mul_f32_e32 v16, v5, v3
	v_mul_f32_e32 v3, 0x3d372713, v2
	v_mul_f32_e32 v3, v2, v3
	v_fma_f32 v3, v2, v3, v2
	v_mul_f32_e32 v3, 0x3fcc422a, v3
	v_mul_f32_e32 v3, 0xbfb8aa3b, v3
	v_exp_f32_e32 v3, v3
	v_lshl_add_u64 v[4:5], v[0:1], 1, s[14:15]
	v_lshl_add_u64 v[0:1], s[16:17], 0, v[0:1]
	v_add_f32_e32 v3, 1.0, v3
	v_rcp_f32_e32 v3, v3
	s_nop 0
	v_mul_f32_e32 v17, v2, v3
	v_mul_f32_e32 v2, 0x3d372713, v7
	v_mul_f32_e32 v2, v7, v2
	v_fma_f32 v2, v7, v2, v7
	v_mul_f32_e32 v2, 0x3fcc422a, v2
	v_mul_f32_e32 v2, 0xbfb8aa3b, v2
	v_exp_f32_e32 v2, v2
	s_nop 0
	v_add_f32_e32 v2, 1.0, v2
	v_rcp_f32_e32 v2, v2
	s_nop 0
	v_mul_f32_e32 v7, v7, v2
	v_cvt_pk_bf16_f32 v2, v6, v16
	v_cvt_pk_bf16_f32 v3, v17, v7
	global_store_dwordx2 v[4:5], v[2:3], off
	v_mov_b32_e32 v2, 0
	v_cvt_pk_fp8_f32 v2, v6, v16
	v_lshl_add_u32 v4, s4, 5, v75
	v_cvt_pk_fp8_f32 v2, v17, v7 op_sel:[0,0,1]
	global_store_dword v[0:1], v2, off
	v_add_u32_e32 v0, v4, v71
	ds_read_b64 v[6:7], v0 offset:33280
	v_mov_b32_e32 v0, v100
	v_mov_b32_e32 v1, v101
	v_mov_b32_e32 v2, v102
	v_mov_b32_e32 v3, v103
	s_waitcnt lgkmcnt(0)
; #define LAS __attribute__((address_space(3)))
; __device__ __forceinline__ unsigned cvt_pk_bf16(float lo, float hi) { unsigned r; asm volatile("v_cvt_pk_bf16_f32 %0, %1, %2" : "=v"(r) : "v"(lo), "v"(hi)); return r; }
; __device__ __forceinline__ unsigned cvt4_fp8(float a, float b, float c, float d) { int v = 0; v = __builtin_amdgcn_cvt_pk_fp8_f32(a, b, v, false); v = __builtin_amdgcn_cvt_pk_fp8_f32(c, d, v, true); return (unsigned)v; }
; __device__ __forceinline__ float bf_lo(unsigned w) { return __uint_as_float(w << 16); }
; __device__ __forceinline__ float bf_hi(unsigned w) { return __uint_as_float(w & 0xffff0000u); }
; __device__ __forceinline__ float gelu_tanh(float y) { const float z = 1.5957691216057308f * (y + 0.044715f * y * y * y); return y * sigm(z); }
; __device__ __forceinline__ void ssm_y_unit(const Params& P, int li, LAS unsigned char* lds, int unit) {
;     ...
;         for (int q = 0; q < 4; ++q) {
;             const int row = 8 * q + 4 * hi, t = 2 * ti + (row >> 4), h0 = row & 15;
;             const u32x2 uu = *(const LAS u32x2*)(lds + SY_U + r32 * SY_UP + t * 32 + h0 * 2);
;             const f32x4 d4 = *(const f32x4*)(dsk + h0);
;             float y0 = acc[4 * q] + d4[0] * bf_lo(uu[0]), y1 = acc[4 * q + 1] + d4[1] * bf_hi(uu[0]), y2 = acc[4 * q + 2] + d4[2] * bf_lo(uu[1]), y3 = acc[4 * q + 3] + d4[3] * bf_hi(uu[1]);
;             const float g0 = gelu_tanh(y0), g1 = gelu_tanh(y1), g2 = gelu_tanh(y2), g3 = gelu_tanh(y3);
;             u32x2 w; w.x = cvt_pk_bf16(g0, g1); w.y = cvt_pk_bf16(g2, g3);
;             const size_t yo = ((size_t)((cg_ * 32 + r32) * 64 + t)) * 1024 + g * 16 + h0;
;             *(u32x2*)(yg + yo) = w; *(unsigned*)(P.ws + WS_YG8 + yo) = cvt4_fp8(g0, g1, g2, g3);
;         }
	v_lshlrev_b32_e32 v5, 16, v6
	v_fma_f32 v0, v0, v5, v8
	v_and_b32_e32 v5, 0xffff0000, v6
	v_fmac_f32_e32 v9, v1, v5
	v_lshlrev_b32_e32 v1, 16, v7
	v_fma_f32 v1, v2, v1, v10
	v_and_b32_e32 v2, 0xffff0000, v7
	v_fmac_f32_e32 v11, v3, v2
	v_mul_f32_e32 v2, 0x3d372713, v0
	v_mul_f32_e32 v2, v0, v2
	v_fma_f32 v2, v0, v2, v0
	v_mul_f32_e32 v2, 0x3fcc422a, v2
	v_mul_f32_e32 v2, 0xbfb8aa3b, v2
	v_exp_f32_e32 v2, v2
	s_nop 0
	v_add_f32_e32 v2, 1.0, v2
	v_rcp_f32_e32 v2, v2
	s_nop 0
	v_mul_f32_e32 v5, v0, v2
	v_mul_f32_e32 v0, 0x3d372713, v9
	v_mul_f32_e32 v0, v9, v0
	v_fma_f32 v0, v9, v0, v9
	v_mul_f32_e32 v0, 0x3fcc422a, v0
	v_mul_f32_e32 v0, 0xbfb8aa3b, v0
	v_exp_f32_e32 v0, v0
	s_nop 0
	v_add_f32_e32 v0, 1.0, v0
	v_rcp_f32_e32 v0, v0
	s_nop 0
	v_mul_f32_e32 v10, v9, v0
	v_mul_f32_e32 v0, 0x3d372713, v1
	v_mul_f32_e32 v0, v1, v0
	v_fma_f32 v0, v1, v0, v1
	v_mul_f32_e32 v0, 0x3fcc422a, v0
	v_mul_f32_e32 v0, 0xbfb8aa3b, v0
	v_exp_f32_e32 v0, v0
	v_cvt_pk_bf16_f32 v6, v5, v10
	s_nop 0
	v_add_f32_e32 v0, 1.0, v0
	v_rcp_f32_e32 v0, v0
	s_nop 0
	v_mul_f32_e32 v16, v1, v0
	v_mul_f32_e32 v0, 0x3d372713, v11
	v_mul_f32_e32 v0, v11, v0
	v_fma_f32 v0, v11, v0, v11
	v_mul_f32_e32 v0, 0x3fcc422a, v0
	v_mul_f32_e32 v0, 0xbfb8aa3b, v0
	v_exp_f32_e32 v0, v0
	s_nop 0
	v_add_f32_e32 v0, 1.0, v0
	v_rcp_f32_e32 v0, v0
	s_nop 0
	v_mul_f32_e32 v11, v11, v0
	v_add_u32_e32 v0, s4, v162
	v_ashrrev_i32_e32 v1, 31, v0
	v_lshlrev_b64 v[0:1], 10, v[0:1]
	v_lshl_add_u64 v[0:1], v[0:1], 0, s[18:19]
	v_or_b32_e32 v2, v0, v66
	v_mov_b32_e32 v3, v1
	v_lshl_add_u64 v[8:9], v[2:3], 1, s[14:15]
	v_cvt_pk_bf16_f32 v7, v16, v11
	global_store_dwordx2 v[8:9], v[6:7], off
	v_mov_b32_e32 v6, 0
	v_cvt_pk_fp8_f32 v6, v5, v10
	v_lshl_add_u64 v[2:3], s[16:17], 0, v[2:3]
	v_or_b32_e32 v0, v0, v70
	v_cvt_pk_fp8_f32 v6, v16, v11 op_sel:[0,0,1]
	global_store_dword v[2:3], v6, off
	v_add_u32_e32 v2, v4, v77
	ds_read_b64 v[6:7], v2 offset:33280
	v_mov_b32_e32 v2, v104
	v_mov_b32_e32 v3, v105
	v_mov_b32_e32 v4, v106
	v_mov_b32_e32 v5, v107
	s_waitcnt lgkmcnt(0)
	v_lshlrev_b32_e32 v8, 16, v6
	v_and_b32_e32 v6, 0xffff0000, v6
	v_fmac_f32_e32 v13, v3, v6
	v_lshlrev_b32_e32 v3, 16, v7
	v_fma_f32 v2, v2, v8, v12
	v_fma_f32 v3, v4, v3, v14
	v_and_b32_e32 v4, 0xffff0000, v7
	v_fmac_f32_e32 v15, v5, v4
	v_mul_f32_e32 v4, 0x3d372713, v2
	v_mul_f32_e32 v4, v2, v4
	v_fma_f32 v4, v2, v4, v2
	v_mul_f32_e32 v4, 0x3fcc422a, v4
	v_mul_f32_e32 v4, 0xbfb8aa3b, v4
	v_exp_f32_e32 v4, v4
	s_nop 0
	v_add_f32_e32 v4, 1.0, v4
	v_rcp_f32_e32 v4, v4
	s_nop 0
	v_mul_f32_e32 v6, v2, v4
	v_mul_f32_e32 v2, 0x3d372713, v13
	v_mul_f32_e32 v2, v13, v2
	v_fma_f32 v2, v13, v2, v13
	v_mul_f32_e32 v2, 0x3fcc422a, v2
	v_mul_f32_e32 v2, 0xbfb8aa3b, v2
	v_exp_f32_e32 v2, v2
	v_lshl_add_u64 v[4:5], v[0:1], 1, s[14:15]
	v_lshl_add_u64 v[0:1], s[16:17], 0, v[0:1]
	v_add_f32_e32 v2, 1.0, v2
	v_rcp_f32_e32 v2, v2
	s_nop 0
	v_mul_f32_e32 v7, v13, v2
	v_mul_f32_e32 v2, 0x3d372713, v3
	v_mul_f32_e32 v2, v3, v2
	v_fma_f32 v2, v3, v2, v3
	v_mul_f32_e32 v2, 0x3fcc422a, v2
	v_mul_f32_e32 v2, 0xbfb8aa3b, v2
	v_exp_f32_e32 v2, v2
	s_nop 0
	v_add_f32_e32 v2, 1.0, v2
	v_rcp_f32_e32 v2, v2
	s_nop 0
	v_mul_f32_e32 v8, v3, v2
	v_mul_f32_e32 v2, 0x3d372713, v15
	v_mul_f32_e32 v2, v15, v2
	v_fma_f32 v2, v15, v2, v15
	v_mul_f32_e32 v2, 0x3fcc422a, v2
	v_mul_f32_e32 v2, 0xbfb8aa3b, v2
	v_exp_f32_e32 v2, v2
	s_nop 0
	v_add_f32_e32 v2, 1.0, v2
	v_rcp_f32_e32 v2, v2
	s_nop 0
	v_mul_f32_e32 v9, v15, v2
	v_cvt_pk_bf16_f32 v2, v6, v7
	v_cvt_pk_bf16_f32 v3, v8, v9
	global_store_dwordx2 v[4:5], v[2:3], off
	v_mov_b32_e32 v2, 0
	v_cvt_pk_fp8_f32 v2, v6, v7
	v_cvt_pk_fp8_f32 v2, v8, v9 op_sel:[0,0,1]
	global_store_dword v[0:1], v2, off
	s_cbranch_scc1 .LBB0_377

; #define LAS __attribute__((address_space(3)))
; __device__ __forceinline__ void ssm_y_unit(const Params& P, int li, LAS unsigned char* lds, int unit) {
;     ...
;     for (int j = 0; j < 4; ++j) {
;         const int ti = (j == 0) ? wid : (j == 1) ? 15 - wid : (j == 2) ? 16 + wid : 31 - wid;
;         f32x16 acc = {};
;         const int ns = 2 * ti + 2;
;         const LAS unsigned char* ub = lds + SY_U + r32 * SY_UP + hi * 16;
;         const LAS unsigned char* kb = lds + SY_KT + hrow * 32 + hi * 16;
;         f32x16 acc2 = {};
;         for (int s = 0; s < ns; s += 2) {
;             int tau = 2 * ti + trow - s; const int tau0 = tau < 0 ? 64 : tau, tau1 = tau - 1 < 0 ? 64 : tau - 1;
;             const bf16x8 a0 = *(const LAS bf16x8*)(kb + tau0 * 512), a1 = *(const LAS bf16x8*)(kb + tau1 * 512);
;             const bf16x8 b0 = *(const LAS bf16x8*)(ub + s * 32), b1 = *(const LAS bf16x8*)(ub + s * 32 + 32);
;             acc = __builtin_amdgcn_mfma_f32_32x32x16_bf16(a0, b0, acc, 0, 0, 0);
;             acc2 = __builtin_amdgcn_mfma_f32_32x32x16_bf16(a1, b1, acc2, 0, 0, 0);
;         }
;         const bf16_t* E = (const bf16_t*)(P.ws + WS_ETAB) + ((size_t)g * 1024 + ti * 32 + r32) * 128 + hi * 8;
; #pragma unroll
;         for (int k = 0; k < 8; k += 2) { const bf16x8 a0 = *(const bf16x8*)(E + k * 16), a1 = *(const bf16x8*)(E + k * 16 + 16);
.LBB0_391:
	s_lshl_b32 s20, s26, 1
	s_lshl_b32 s40, s26, 5
	s_ashr_i32 s41, s40, 31
	v_lshl_add_u64 v[140:141], v[64:65], 0, s[40:41]
	v_lshlrev_b64 v[140:141], 8, v[140:141]
	v_lshl_add_u64 v[140:141], v[72:73], 0, v[140:141]
	global_load_dwordx4 v[108:111], v[140:141], off
	global_load_dwordx4 v[112:115], v[140:141], off offset:32
	global_load_dwordx4 v[116:119], v[140:141], off offset:64
	global_load_dwordx4 v[120:123], v[140:141], off offset:96
	global_load_dwordx4 v[124:127], v[140:141], off offset:128
	global_load_dwordx4 v[128:131], v[140:141], off offset:160
	global_load_dwordx4 v[132:135], v[140:141], off offset:192
	global_load_dwordx4 v[136:139], v[140:141], off offset:224
	v_mov_b32_e32 v15, 0
	s_cmp_lt_i32 s26, 0
	v_mov_b32_e32 v14, v15
	v_mov_b32_e32 v13, v15
	v_mov_b32_e32 v12, v15
	v_mov_b32_e32 v11, v15
	v_mov_b32_e32 v10, v15
	v_mov_b32_e32 v9, v15
	v_mov_b32_e32 v8, v15
	v_mov_b32_e32 v7, v15
	v_mov_b32_e32 v6, v15
	v_mov_b32_e32 v5, v15
	v_mov_b32_e32 v4, v15
	v_mov_b32_e32 v3, v15
	v_mov_b32_e32 v2, v15
	v_mov_b32_e32 v1, v15
	v_mov_b32_e32 v0, v15
	v_mov_b32_e32 v31, v15
	v_mov_b32_e32 v30, v15
	v_mov_b32_e32 v29, v15
	v_mov_b32_e32 v28, v15
	v_mov_b32_e32 v27, v15
	v_mov_b32_e32 v26, v15
	v_mov_b32_e32 v25, v15
	v_mov_b32_e32 v24, v15
	v_mov_b32_e32 v23, v15
	v_mov_b32_e32 v22, v15
	v_mov_b32_e32 v21, v15
	v_mov_b32_e32 v20, v15
	v_mov_b32_e32 v19, v15
	v_mov_b32_e32 v18, v15
	v_mov_b32_e32 v17, v15
	v_mov_b32_e32 v16, v15
	s_cbranch_scc1 .LBB0_385
	v_mov_b32_e32 v0, 0
	v_lshl_or_b32 v80, s26, 10, v79
	v_add_u32_e32 v81, s20, v74
	s_mov_b32 s21, -2
	v_mov_b32_e32 v82, v78
	v_mov_b32_e32 v1, v0
	v_mov_b32_e32 v2, v0
	v_mov_b32_e32 v3, v0
	v_mov_b32_e32 v4, v0
	v_mov_b32_e32 v5, v0
	v_mov_b32_e32 v6, v0
	v_mov_b32_e32 v7, v0
	v_mov_b32_e32 v8, v0
	v_mov_b32_e32 v9, v0
	v_mov_b32_e32 v10, v0
	v_mov_b32_e32 v11, v0
	v_mov_b32_e32 v12, v0
	v_mov_b32_e32 v13, v0
	v_mov_b32_e32 v14, v0
	v_mov_b32_e32 v15, v0
	v_mov_b32_e32 v16, v0
	v_mov_b32_e32 v17, v0
	v_mov_b32_e32 v18, v0
	v_mov_b32_e32 v19, v0
	v_mov_b32_e32 v20, v0
	v_mov_b32_e32 v21, v0
	v_mov_b32_e32 v22, v0
	v_mov_b32_e32 v23, v0
	v_mov_b32_e32 v24, v0
	v_mov_b32_e32 v25, v0
	v_mov_b32_e32 v26, v0
	v_mov_b32_e32 v27, v0
	v_mov_b32_e32 v28, v0
	v_mov_b32_e32 v29, v0
	v_mov_b32_e32 v30, v0
	v_mov_b32_e32 v31, v0

;     __device__ void init(int M, int N, int G_, int c_, unsigned long long mask_ = 0ull) { nM = M / BM; nN = mask_ ? __builtin_popcountll(mask_) : N / BM; nwg = nM * nN; G = G_; c = c_; mask = mask_; }
; #define LAUNDER() do { tid = threadIdx.x; asm volatile("" : "+v"(tid)); lane = tid & 63; wid = __builtin_amdgcn_readfirstlane(tid >> 6); bx = blockIdx.x; asm volatile("" : "+s"(bx)); \
;         vcu = (G % 8 == 0) ? (bx % 8) * (G / 8) + bx / 8 : bx; gw = vcu * 8 + wid; ws = P.ws; asm volatile("" : "+s"(ws)); Q.ws = ws; XB = (bf16_t*)(ws + WS_XB); } while (0)
; __global__ void __launch_bounds__(512, 2) trunk_fwd(Params P) {
;     ...
;         LAUNDER();
;         if (PH(9)) {   pg8::Gemm g{(const bf16_t*)(ws + WS_ZA), (const bf16_t*)(ws + WS_WAO), T, DM, AW}; pg8::StaticOrder S; S.init(T, DM, G, bx);
;             Epi<EPI_MRG_A> E{}; E.O = (bf16_t*)(ws + WS_GA); E.ldc = DM;
;             pg8::gemm_phase(lds, g, S, E); }
.LBB0_572:
	s_or_b64 exec, exec, s[2:3]
	s_waitcnt lgkmcnt(0)
	v_mov_b32_e32 v0, v160
	v_readlane_b32 s20, v252, 50
	s_mov_b64 s[42:43], s[44:45]
	s_barrier
	s_bitcmp1_b32 s20, 0
	s_cbranch_scc0 .Lstagger_p6_done
	s_sleep 127
	s_sleep 127
	s_sleep 127
	s_sleep 127
.Lstagger_p6_done:
	s_add_u32 s36, s42, 0x1d400000
	s_addc_u32 s37, s43, 0
	v_mov_b32_e32 v8, v160
	s_cmpk_lt_i32 s20, 0x400
	s_cselect_b64 s[40:41], -1, 0
	s_cmpk_gt_i32 s20, 0x3ff
	v_readfirstlane_b32 s18, v8
	s_cbranch_scc1 .LBB0_596
	s_ashr_i32 s10, s20, 31
	s_lshr_b32 s0, s10, 29
	s_add_i32 s0, s20, s0
	s_and_b32 s1, s0, -8
	s_sub_i32 s1, s20, s1
	s_cmp_gt_i32 s1, -1
	s_mov_b64 s[2:3], -1
	s_cbranch_scc0 .LBB0_575
	s_lshl_b32 s4, s1, 7
	s_mov_b64 s[2:3], 0
